# attention QK^T section: K fragment reads through a 13-buffer register ring issued 12 ahead of the MFMAs (both attention layers)
# speedup vs baseline: 1.0237x; 1.0029x over previous
.LBB0_662:
	s_add_i32 s0, s16, s12
	s_cmp_gt_i32 s0, s17
	s_cselect_b32 s13, 2, 0
	s_cmp_lt_i32 s0, s17
	s_cselect_b64 s[0:1], -1, 0
	s_and_b64 s[22:23], s[0:1], exec
	s_cselect_b32 s24, 1, s13
	s_cmp_lt_i32 s12, s18
	s_cselect_b64 s[12:13], -1, 0
	s_and_b64 s[22:23], s[12:13], exec
	s_cselect_b32 s22, s24, 0
	s_cmp_lg_u32 s22, 0
	ds_read_b128 v[134:137], v180
	ds_read_b128 v[138:141], v180 offset:64
	ds_read_b128 v[142:145], v180 offset:128
	ds_read_b128 v[200:203], v180 offset:192
	ds_read_b128 v[204:207], v180 offset:4608
	ds_read_b128 v[216:219], v180 offset:4672
	ds_read_b128 v[220:223], v180 offset:4736
	ds_read_b128 v[224:227], v180 offset:4800
	ds_read_b128 v[228:231], v180 offset:9216
	ds_read_b128 v[232:235], v180 offset:9280
	ds_read_b128 v[236:239], v180 offset:9344
	ds_read_b128 v[240:243], v180 offset:9408
	s_waitcnt lgkmcnt(11)
	v_mfma_f32_16x16x32_bf16 v[86:89], v[134:137], v[2:5], 0
	ds_read_b128 v[244:247], v180 offset:13824
	s_waitcnt lgkmcnt(11)
	v_mfma_f32_16x16x32_bf16 v[86:89], v[138:141], v[6:9], v[86:89]
	ds_read_b128 v[134:137], v180 offset:13888
	s_waitcnt lgkmcnt(11)
	v_mfma_f32_16x16x32_bf16 v[86:89], v[142:145], v[10:13], v[86:89]
	ds_read_b128 v[138:141], v180 offset:13952
	s_waitcnt lgkmcnt(11)
	v_mfma_f32_16x16x32_bf16 v[86:89], v[200:203], v[14:17], v[86:89]
	ds_read_b128 v[142:145], v180 offset:14016
	s_waitcnt lgkmcnt(11)
	v_mfma_f32_16x16x32_bf16 v[82:85], v[204:207], v[2:5], 0
	ds_read_b128 v[200:203], v180 offset:18432
	s_waitcnt lgkmcnt(11)
	v_mfma_f32_16x16x32_bf16 v[82:85], v[216:219], v[6:9], v[82:85]
	ds_read_b128 v[204:207], v180 offset:18496
	s_waitcnt lgkmcnt(11)
	v_mfma_f32_16x16x32_bf16 v[82:85], v[220:223], v[10:13], v[82:85]
	ds_read_b128 v[216:219], v180 offset:18560
	s_waitcnt lgkmcnt(11)
	v_mfma_f32_16x16x32_bf16 v[82:85], v[224:227], v[14:17], v[82:85]
	ds_read_b128 v[220:223], v180 offset:18624
	s_waitcnt lgkmcnt(11)
	v_mfma_f32_16x16x32_bf16 v[90:93], v[228:231], v[2:5], 0
	ds_read_b128 v[224:227], v180 offset:23040
	s_waitcnt lgkmcnt(11)
	v_mfma_f32_16x16x32_bf16 v[90:93], v[232:235], v[6:9], v[90:93]
	ds_read_b128 v[228:231], v180 offset:23104
	s_waitcnt lgkmcnt(11)
	v_mfma_f32_16x16x32_bf16 v[90:93], v[236:239], v[10:13], v[90:93]
	ds_read_b128 v[232:235], v180 offset:23168
	s_waitcnt lgkmcnt(11)
	v_mfma_f32_16x16x32_bf16 v[90:93], v[240:243], v[14:17], v[90:93]
	ds_read_b128 v[236:239], v180 offset:23232
	s_waitcnt lgkmcnt(11)
	v_mfma_f32_16x16x32_bf16 v[94:97], v[244:247], v[2:5], 0
	ds_read_b128 v[240:243], v180 offset:27648
	s_waitcnt lgkmcnt(11)
	v_mfma_f32_16x16x32_bf16 v[94:97], v[134:137], v[6:9], v[94:97]
	ds_read_b128 v[244:247], v180 offset:27712
	s_waitcnt lgkmcnt(11)
	v_mfma_f32_16x16x32_bf16 v[94:97], v[138:141], v[10:13], v[94:97]
	ds_read_b128 v[134:137], v180 offset:27776
	s_waitcnt lgkmcnt(11)
	v_mfma_f32_16x16x32_bf16 v[94:97], v[142:145], v[14:17], v[94:97]
	ds_read_b128 v[138:141], v180 offset:27840
	s_waitcnt lgkmcnt(11)
	v_mfma_f32_16x16x32_bf16 v[98:101], v[200:203], v[2:5], 0
	ds_read_b128 v[142:145], v180 offset:32256
	s_waitcnt lgkmcnt(11)
	v_mfma_f32_16x16x32_bf16 v[98:101], v[204:207], v[6:9], v[98:101]
	ds_read_b128 v[200:203], v180 offset:32320
	s_waitcnt lgkmcnt(11)
	v_mfma_f32_16x16x32_bf16 v[98:101], v[216:219], v[10:13], v[98:101]
	ds_read_b128 v[204:207], v180 offset:32384
	s_waitcnt lgkmcnt(11)
	v_mfma_f32_16x16x32_bf16 v[98:101], v[220:223], v[14:17], v[98:101]
	ds_read_b128 v[216:219], v180 offset:32448
	s_waitcnt lgkmcnt(11)
	v_mfma_f32_16x16x32_bf16 v[102:105], v[224:227], v[2:5], 0
	s_waitcnt lgkmcnt(10)
	v_mfma_f32_16x16x32_bf16 v[102:105], v[228:231], v[6:9], v[102:105]
	s_waitcnt lgkmcnt(9)
	v_mfma_f32_16x16x32_bf16 v[102:105], v[232:235], v[10:13], v[102:105]
	s_waitcnt lgkmcnt(8)
	v_mfma_f32_16x16x32_bf16 v[102:105], v[236:239], v[14:17], v[102:105]
	s_waitcnt lgkmcnt(7)
	v_mfma_f32_16x16x32_bf16 v[106:109], v[240:243], v[2:5], 0
	s_waitcnt lgkmcnt(6)
	v_mfma_f32_16x16x32_bf16 v[106:109], v[244:247], v[6:9], v[106:109]
	s_waitcnt lgkmcnt(5)
	v_mfma_f32_16x16x32_bf16 v[106:109], v[134:137], v[10:13], v[106:109]
	s_waitcnt lgkmcnt(4)
	v_mfma_f32_16x16x32_bf16 v[106:109], v[138:141], v[14:17], v[106:109]
	s_waitcnt lgkmcnt(3)
	v_mfma_f32_16x16x32_bf16 v[110:113], v[142:145], v[2:5], 0
	s_waitcnt lgkmcnt(2)
	v_mfma_f32_16x16x32_bf16 v[110:113], v[200:203], v[6:9], v[110:113]
	s_waitcnt lgkmcnt(1)
	v_mfma_f32_16x16x32_bf16 v[110:113], v[204:207], v[10:13], v[110:113]
	s_waitcnt lgkmcnt(0)
	v_mfma_f32_16x16x32_bf16 v[110:113], v[216:219], v[14:17], v[110:113]
	s_cbranch_scc0 .LBB0_667
	s_and_b64 vcc, s[12:13], s[0:1]
	s_cmp_eq_u32 s22, 2
	s_cselect_b64 s[0:1], -1, 0
	s_nop 0
	v_cndmask_b32_e64 v134, v184, v1, s[0:1]
	v_cndmask_b32_e32 v136, 0, v1, vcc
	v_cndmask_b32_e32 v195, v134, v171, vcc
	v_sub_u32_e32 v196, v114, v136
	v_pk_mul_f32 v[134:135], v[86:87], s[10:11] op_sel_hi:[1,0]
	v_add_u32_e32 v137, 1, v196
	v_cmp_le_u32_e32 vcc, v196, v195
	v_add_u32_e32 v140, 3, v196
	v_add_u32_e32 v139, 2, v196
	v_cndmask_b32_e32 v136, v185, v134, vcc
	v_cmp_le_u32_e32 vcc, v137, v195
	v_add_u32_e32 v141, 19, v196
	v_add_u32_e32 v146, 33, v196
	v_cndmask_b32_e32 v137, v185, v135, vcc
	v_pk_mul_f32 v[134:135], v[88:89], s[10:11] op_sel_hi:[1,0]
	v_cmp_le_u32_e32 vcc, v140, v195
	v_add_u32_e32 v140, 17, v196
	v_max3_f32 v138, v194, v136, v137
	v_cndmask_b32_e32 v143, v185, v135, vcc
	v_cmp_le_u32_e32 vcc, v139, v195
	v_add_u32_e32 v139, 16, v196
	v_add_u32_e32 v145, 32, v196
	v_cndmask_b32_e32 v142, v185, v134, vcc
	v_pk_mul_f32 v[134:135], v[82:83], s[10:11] op_sel_hi:[1,0]
	v_cmp_le_u32_e32 vcc, v140, v195
	v_max3_f32 v138, v138, v142, v143
	v_add_u32_e32 v140, 18, v196
	v_cndmask_b32_e32 v135, v185, v135, vcc
	v_cmp_le_u32_e32 vcc, v139, v195
	v_add_u32_e32 v147, 35, v196
	v_add_u32_e32 v150, 49, v196
	v_cndmask_b32_e32 v134, v185, v134, vcc
	v_max3_f32 v144, v138, v134, v135
	v_pk_mul_f32 v[138:139], v[84:85], s[10:11] op_sel_hi:[1,0]
	v_cmp_le_u32_e32 vcc, v141, v195
	v_add_u32_e32 v149, 48, v196
	v_add_u32_e32 v151, 51, v196
	v_cndmask_b32_e32 v141, v185, v139, vcc
	v_cmp_le_u32_e32 vcc, v140, v195
	v_add_u32_e32 v154, 0x41, v196
	v_add_u32_e32 v153, 64, v196
	v_cndmask_b32_e32 v140, v185, v138, vcc
	v_pk_mul_f32 v[138:139], v[90:91], s[10:11] op_sel_hi:[1,0]
	v_cmp_le_u32_e32 vcc, v146, v195
	v_max3_f32 v144, v144, v140, v141
	v_add_u32_e32 v146, 34, v196
	v_cndmask_b32_e32 v139, v185, v139, vcc
	v_cmp_le_u32_e32 vcc, v145, v195
	v_add_u32_e32 v155, 0x43, v196
	v_add_u32_e32 v158, 0x51, v196
	v_cndmask_b32_e32 v138, v185, v138, vcc
	v_max3_f32 v148, v144, v138, v139
	v_pk_mul_f32 v[144:145], v[92:93], s[10:11] op_sel_hi:[1,0]
	v_cmp_le_u32_e32 vcc, v147, v195
	v_add_u32_e32 v157, 0x50, v196
	v_add_u32_e32 v159, 0x53, v196
	v_cndmask_b32_e32 v147, v185, v145, vcc
	v_cmp_le_u32_e32 vcc, v146, v195
	v_add_u32_e32 v162, 0x61, v196
	v_add_u32_e32 v161, 0x60, v196
	v_cndmask_b32_e32 v146, v185, v144, vcc
	v_pk_mul_f32 v[144:145], v[94:95], s[10:11] op_sel_hi:[1,0]
	v_cmp_le_u32_e32 vcc, v150, v195
	v_max3_f32 v148, v148, v146, v147
	v_add_u32_e32 v150, 50, v196
	v_cndmask_b32_e32 v145, v185, v145, vcc
	v_cmp_le_u32_e32 vcc, v149, v195
	v_add_u32_e32 v164, 0x63, v196
	v_add_u32_e32 v163, 0x62, v196
	v_cndmask_b32_e32 v144, v185, v144, vcc
	v_max3_f32 v152, v148, v144, v145
	v_pk_mul_f32 v[148:149], v[96:97], s[10:11] op_sel_hi:[1,0]
	v_cmp_le_u32_e32 vcc, v151, v195
	v_add_u32_e32 v197, 0x71, v196
	v_add_u32_e32 v165, 0x70, v196
	v_cndmask_b32_e32 v151, v185, v149, vcc
	v_cmp_le_u32_e32 vcc, v150, v195
	v_add_u32_e32 v198, 0x72, v196
	s_nop 0
	v_cndmask_b32_e32 v150, v185, v148, vcc
	v_pk_mul_f32 v[148:149], v[98:99], s[10:11] op_sel_hi:[1,0]
	v_cmp_le_u32_e32 vcc, v154, v195
	v_max3_f32 v152, v152, v150, v151
	v_add_u32_e32 v154, 0x42, v196
	v_cndmask_b32_e32 v149, v185, v149, vcc
	v_cmp_le_u32_e32 vcc, v153, v195
	s_nop 1
	v_cndmask_b32_e32 v148, v185, v148, vcc
	v_max3_f32 v156, v152, v148, v149
	v_pk_mul_f32 v[152:153], v[100:101], s[10:11] op_sel_hi:[1,0]
	v_cmp_le_u32_e32 vcc, v155, v195
	s_nop 1
	v_cndmask_b32_e32 v155, v185, v153, vcc
	v_cmp_le_u32_e32 vcc, v154, v195
	s_nop 1
	v_cndmask_b32_e32 v154, v185, v152, vcc
	v_pk_mul_f32 v[152:153], v[102:103], s[10:11] op_sel_hi:[1,0]
	v_cmp_le_u32_e32 vcc, v158, v195
	v_max3_f32 v156, v156, v154, v155
	v_add_u32_e32 v158, 0x52, v196
	v_cndmask_b32_e32 v153, v185, v153, vcc
	v_cmp_le_u32_e32 vcc, v157, v195
	v_add_u32_e32 v196, 0x73, v196
	s_nop 0
	v_cndmask_b32_e32 v152, v185, v152, vcc
	v_max3_f32 v160, v156, v152, v153
	v_pk_mul_f32 v[156:157], v[104:105], s[10:11] op_sel_hi:[1,0]
	v_cmp_le_u32_e32 vcc, v159, v195
	s_nop 1
	v_cndmask_b32_e32 v159, v185, v157, vcc
	v_cmp_le_u32_e32 vcc, v158, v195
	s_nop 1
	v_cndmask_b32_e32 v158, v185, v156, vcc
	v_pk_mul_f32 v[156:157], v[106:107], s[10:11] op_sel_hi:[1,0]
	v_cmp_le_u32_e32 vcc, v162, v195
	v_max3_f32 v160, v160, v158, v159
	s_nop 0
	v_cndmask_b32_e32 v157, v185, v157, vcc
	v_cmp_le_u32_e32 vcc, v161, v195
	s_nop 1
	v_cndmask_b32_e32 v156, v185, v156, vcc
	v_max3_f32 v162, v160, v156, v157
	v_pk_mul_f32 v[160:161], v[108:109], s[10:11] op_sel_hi:[1,0]
	v_cmp_le_u32_e32 vcc, v164, v195
	s_nop 1
	v_cndmask_b32_e32 v161, v185, v161, vcc
	v_cmp_le_u32_e32 vcc, v163, v195
	s_nop 1
	v_cndmask_b32_e32 v160, v185, v160, vcc
	v_max3_f32 v164, v162, v160, v161
	v_pk_mul_f32 v[162:163], v[110:111], s[10:11] op_sel_hi:[1,0]
	v_cmp_le_u32_e32 vcc, v197, v195
	s_nop 1
	v_cndmask_b32_e32 v163, v185, v163, vcc
	v_cmp_le_u32_e32 vcc, v165, v195
	s_nop 1
	v_cndmask_b32_e32 v162, v185, v162, vcc
	v_max3_f32 v197, v164, v162, v163
	v_pk_mul_f32 v[164:165], v[112:113], s[10:11] op_sel_hi:[1,0]
	v_cmp_le_u32_e32 vcc, v196, v195
	s_nop 1
	v_cndmask_b32_e32 v165, v185, v165, vcc
	v_cmp_le_u32_e32 vcc, v198, v195
	s_nop 1
	v_cndmask_b32_e32 v164, v185, v164, vcc
	v_max3_f32 v195, v197, v164, v165
	s_cbranch_execnz .LBB0_665

.LBB0_2559:
	s_add_i32 s0, s12, s16
	s_cmp_gt_u32 s0, s20
	s_cselect_b32 s17, 2, 0
	s_cmp_lt_u32 s0, s20
	s_cselect_b64 s[0:1], -1, 0
	s_and_b64 s[28:29], s[0:1], exec
	s_cselect_b32 s30, 1, s17
	s_cmp_le_i32 s16, s23
	s_cselect_b64 s[16:17], -1, 0
	s_and_b64 s[28:29], s[16:17], exec
	s_cselect_b32 s28, s30, 0
	s_cmp_lg_u32 s28, 0
	ds_read_b128 v[134:137], v181
	ds_read_b128 v[138:141], v181 offset:64
	ds_read_b128 v[142:145], v181 offset:128
	ds_read_b128 v[200:203], v181 offset:192
	ds_read_b128 v[204:207], v181 offset:4608
	ds_read_b128 v[216:219], v181 offset:4672
	ds_read_b128 v[220:223], v181 offset:4736
	ds_read_b128 v[224:227], v181 offset:4800
	ds_read_b128 v[228:231], v181 offset:9216
	ds_read_b128 v[232:235], v181 offset:9280
	ds_read_b128 v[236:239], v181 offset:9344
	ds_read_b128 v[240:243], v181 offset:9408
	s_waitcnt lgkmcnt(11)
	v_mfma_f32_16x16x32_bf16 v[86:89], v[134:137], v[2:5], 0
	ds_read_b128 v[244:247], v181 offset:13824
	s_waitcnt lgkmcnt(11)
	v_mfma_f32_16x16x32_bf16 v[86:89], v[138:141], v[6:9], v[86:89]
	ds_read_b128 v[134:137], v181 offset:13888
	s_waitcnt lgkmcnt(11)
	v_mfma_f32_16x16x32_bf16 v[86:89], v[142:145], v[10:13], v[86:89]
	ds_read_b128 v[138:141], v181 offset:13952
	s_waitcnt lgkmcnt(11)
	v_mfma_f32_16x16x32_bf16 v[86:89], v[200:203], v[14:17], v[86:89]
	ds_read_b128 v[142:145], v181 offset:14016
	s_waitcnt lgkmcnt(11)
	v_mfma_f32_16x16x32_bf16 v[82:85], v[204:207], v[2:5], 0
	ds_read_b128 v[200:203], v181 offset:18432
	s_waitcnt lgkmcnt(11)
	v_mfma_f32_16x16x32_bf16 v[82:85], v[216:219], v[6:9], v[82:85]
	ds_read_b128 v[204:207], v181 offset:18496
	s_waitcnt lgkmcnt(11)
	v_mfma_f32_16x16x32_bf16 v[82:85], v[220:223], v[10:13], v[82:85]
	ds_read_b128 v[216:219], v181 offset:18560
	s_waitcnt lgkmcnt(11)
	v_mfma_f32_16x16x32_bf16 v[82:85], v[224:227], v[14:17], v[82:85]
	ds_read_b128 v[220:223], v181 offset:18624
	s_waitcnt lgkmcnt(11)
	v_mfma_f32_16x16x32_bf16 v[90:93], v[228:231], v[2:5], 0
	ds_read_b128 v[224:227], v181 offset:23040
	s_waitcnt lgkmcnt(11)
	v_mfma_f32_16x16x32_bf16 v[90:93], v[232:235], v[6:9], v[90:93]
	ds_read_b128 v[228:231], v181 offset:23104
	s_waitcnt lgkmcnt(11)
	v_mfma_f32_16x16x32_bf16 v[90:93], v[236:239], v[10:13], v[90:93]
	ds_read_b128 v[232:235], v181 offset:23168
	s_waitcnt lgkmcnt(11)
	v_mfma_f32_16x16x32_bf16 v[90:93], v[240:243], v[14:17], v[90:93]
	ds_read_b128 v[236:239], v181 offset:23232
	s_waitcnt lgkmcnt(11)
	v_mfma_f32_16x16x32_bf16 v[94:97], v[244:247], v[2:5], 0
	ds_read_b128 v[240:243], v181 offset:27648
	s_waitcnt lgkmcnt(11)
	v_mfma_f32_16x16x32_bf16 v[94:97], v[134:137], v[6:9], v[94:97]
	ds_read_b128 v[244:247], v181 offset:27712
	s_waitcnt lgkmcnt(11)
	v_mfma_f32_16x16x32_bf16 v[94:97], v[138:141], v[10:13], v[94:97]
	ds_read_b128 v[134:137], v181 offset:27776
	s_waitcnt lgkmcnt(11)
	v_mfma_f32_16x16x32_bf16 v[94:97], v[142:145], v[14:17], v[94:97]
	ds_read_b128 v[138:141], v181 offset:27840
	s_waitcnt lgkmcnt(11)
	v_mfma_f32_16x16x32_bf16 v[98:101], v[200:203], v[2:5], 0
	ds_read_b128 v[142:145], v181 offset:32256
	s_waitcnt lgkmcnt(11)
	v_mfma_f32_16x16x32_bf16 v[98:101], v[204:207], v[6:9], v[98:101]
	ds_read_b128 v[200:203], v181 offset:32320
	s_waitcnt lgkmcnt(11)
	v_mfma_f32_16x16x32_bf16 v[98:101], v[216:219], v[10:13], v[98:101]
	ds_read_b128 v[204:207], v181 offset:32384
	s_waitcnt lgkmcnt(11)
	v_mfma_f32_16x16x32_bf16 v[98:101], v[220:223], v[14:17], v[98:101]
	ds_read_b128 v[216:219], v181 offset:32448
	s_waitcnt lgkmcnt(11)
	v_mfma_f32_16x16x32_bf16 v[102:105], v[224:227], v[2:5], 0
	s_waitcnt lgkmcnt(10)
	v_mfma_f32_16x16x32_bf16 v[102:105], v[228:231], v[6:9], v[102:105]
	s_waitcnt lgkmcnt(9)
	v_mfma_f32_16x16x32_bf16 v[102:105], v[232:235], v[10:13], v[102:105]
	s_waitcnt lgkmcnt(8)
	v_mfma_f32_16x16x32_bf16 v[102:105], v[236:239], v[14:17], v[102:105]
	s_waitcnt lgkmcnt(7)
	v_mfma_f32_16x16x32_bf16 v[106:109], v[240:243], v[2:5], 0
	s_waitcnt lgkmcnt(6)
	v_mfma_f32_16x16x32_bf16 v[106:109], v[244:247], v[6:9], v[106:109]
	s_waitcnt lgkmcnt(5)
	v_mfma_f32_16x16x32_bf16 v[106:109], v[134:137], v[10:13], v[106:109]
	s_waitcnt lgkmcnt(4)
	v_mfma_f32_16x16x32_bf16 v[106:109], v[138:141], v[14:17], v[106:109]
	s_waitcnt lgkmcnt(3)
	v_mfma_f32_16x16x32_bf16 v[110:113], v[142:145], v[2:5], 0
	s_waitcnt lgkmcnt(2)
	v_mfma_f32_16x16x32_bf16 v[110:113], v[200:203], v[6:9], v[110:113]
	s_waitcnt lgkmcnt(1)
	v_mfma_f32_16x16x32_bf16 v[110:113], v[204:207], v[10:13], v[110:113]
	s_waitcnt lgkmcnt(0)
	v_mfma_f32_16x16x32_bf16 v[110:113], v[216:219], v[14:17], v[110:113]
	s_cbranch_scc0 .LBB0_2564
	s_and_b64 vcc, s[16:17], s[0:1]
	s_cmp_eq_u32 s28, 2
	s_cselect_b64 s[0:1], -1, 0
	s_nop 0
	v_cndmask_b32_e64 v134, v184, v166, s[0:1]
	v_cndmask_b32_e32 v136, 0, v166, vcc
	v_cndmask_b32_e32 v195, v134, v172, vcc
	v_sub_u32_e32 v196, v114, v136
	v_pk_mul_f32 v[134:135], v[86:87], s[14:15] op_sel_hi:[1,0]
	v_add_u32_e32 v137, 1, v196
	v_cmp_le_u32_e32 vcc, v196, v195
	v_add_u32_e32 v140, 3, v196
	v_add_u32_e32 v139, 2, v196
	v_cndmask_b32_e32 v136, v185, v134, vcc
	v_cmp_le_u32_e32 vcc, v137, v195
	v_add_u32_e32 v141, 19, v196
	v_add_u32_e32 v146, 33, v196
	v_cndmask_b32_e32 v137, v185, v135, vcc
	v_pk_mul_f32 v[134:135], v[88:89], s[14:15] op_sel_hi:[1,0]
	v_cmp_le_u32_e32 vcc, v140, v195
	v_add_u32_e32 v140, 17, v196
	v_max3_f32 v138, v194, v136, v137
	v_cndmask_b32_e32 v143, v185, v135, vcc
	v_cmp_le_u32_e32 vcc, v139, v195
	v_add_u32_e32 v139, 16, v196
	v_add_u32_e32 v145, 32, v196
	v_cndmask_b32_e32 v142, v185, v134, vcc
	v_pk_mul_f32 v[134:135], v[82:83], s[14:15] op_sel_hi:[1,0]
	v_cmp_le_u32_e32 vcc, v140, v195
	v_max3_f32 v138, v138, v142, v143
	v_add_u32_e32 v140, 18, v196
	v_cndmask_b32_e32 v135, v185, v135, vcc
	v_cmp_le_u32_e32 vcc, v139, v195
	v_add_u32_e32 v147, 35, v196
	v_add_u32_e32 v150, 49, v196
	v_cndmask_b32_e32 v134, v185, v134, vcc
	v_max3_f32 v144, v138, v134, v135
	v_pk_mul_f32 v[138:139], v[84:85], s[14:15] op_sel_hi:[1,0]
	v_cmp_le_u32_e32 vcc, v141, v195
	v_add_u32_e32 v149, 48, v196
	v_add_u32_e32 v151, 51, v196
	v_cndmask_b32_e32 v141, v185, v139, vcc
	v_cmp_le_u32_e32 vcc, v140, v195
	v_add_u32_e32 v154, 0x41, v196
	v_add_u32_e32 v153, 64, v196
	v_cndmask_b32_e32 v140, v185, v138, vcc
	v_pk_mul_f32 v[138:139], v[90:91], s[14:15] op_sel_hi:[1,0]
	v_cmp_le_u32_e32 vcc, v146, v195
	v_max3_f32 v144, v144, v140, v141
	v_add_u32_e32 v146, 34, v196
	v_cndmask_b32_e32 v139, v185, v139, vcc
	v_cmp_le_u32_e32 vcc, v145, v195
	v_add_u32_e32 v155, 0x43, v196
	v_add_u32_e32 v158, 0x51, v196
	v_cndmask_b32_e32 v138, v185, v138, vcc
	v_max3_f32 v148, v144, v138, v139
	v_pk_mul_f32 v[144:145], v[92:93], s[14:15] op_sel_hi:[1,0]
	v_cmp_le_u32_e32 vcc, v147, v195
	v_add_u32_e32 v157, 0x50, v196
	v_add_u32_e32 v159, 0x53, v196
	v_cndmask_b32_e32 v147, v185, v145, vcc
	v_cmp_le_u32_e32 vcc, v146, v195
	v_add_u32_e32 v162, 0x61, v196
	v_add_u32_e32 v161, 0x60, v196
	v_cndmask_b32_e32 v146, v185, v144, vcc
	v_pk_mul_f32 v[144:145], v[94:95], s[14:15] op_sel_hi:[1,0]
	v_cmp_le_u32_e32 vcc, v150, v195
	v_max3_f32 v148, v148, v146, v147
	v_add_u32_e32 v150, 50, v196
	v_cndmask_b32_e32 v145, v185, v145, vcc
	v_cmp_le_u32_e32 vcc, v149, v195
	v_add_u32_e32 v164, 0x63, v196
	v_add_u32_e32 v163, 0x62, v196
	v_cndmask_b32_e32 v144, v185, v144, vcc
	v_max3_f32 v152, v148, v144, v145
	v_pk_mul_f32 v[148:149], v[96:97], s[14:15] op_sel_hi:[1,0]
	v_cmp_le_u32_e32 vcc, v151, v195
	v_add_u32_e32 v197, 0x71, v196
	v_add_u32_e32 v165, 0x70, v196
	v_cndmask_b32_e32 v151, v185, v149, vcc
	v_cmp_le_u32_e32 vcc, v150, v195
	v_add_u32_e32 v198, 0x72, v196
	s_nop 0
	v_cndmask_b32_e32 v150, v185, v148, vcc
	v_pk_mul_f32 v[148:149], v[98:99], s[14:15] op_sel_hi:[1,0]
	v_cmp_le_u32_e32 vcc, v154, v195
	v_max3_f32 v152, v152, v150, v151
	v_add_u32_e32 v154, 0x42, v196
	v_cndmask_b32_e32 v149, v185, v149, vcc
	v_cmp_le_u32_e32 vcc, v153, v195
	s_nop 1
	v_cndmask_b32_e32 v148, v185, v148, vcc
	v_max3_f32 v156, v152, v148, v149
	v_pk_mul_f32 v[152:153], v[100:101], s[14:15] op_sel_hi:[1,0]
	v_cmp_le_u32_e32 vcc, v155, v195
	s_nop 1
	v_cndmask_b32_e32 v155, v185, v153, vcc
	v_cmp_le_u32_e32 vcc, v154, v195
	s_nop 1
	v_cndmask_b32_e32 v154, v185, v152, vcc
	v_pk_mul_f32 v[152:153], v[102:103], s[14:15] op_sel_hi:[1,0]
	v_cmp_le_u32_e32 vcc, v158, v195
	v_max3_f32 v156, v156, v154, v155
	v_add_u32_e32 v158, 0x52, v196
	v_cndmask_b32_e32 v153, v185, v153, vcc
	v_cmp_le_u32_e32 vcc, v157, v195
	v_add_u32_e32 v196, 0x73, v196
	s_nop 0
	v_cndmask_b32_e32 v152, v185, v152, vcc
	v_max3_f32 v160, v156, v152, v153
	v_pk_mul_f32 v[156:157], v[104:105], s[14:15] op_sel_hi:[1,0]
	v_cmp_le_u32_e32 vcc, v159, v195
	s_nop 1
	v_cndmask_b32_e32 v159, v185, v157, vcc
	v_cmp_le_u32_e32 vcc, v158, v195
	s_nop 1
	v_cndmask_b32_e32 v158, v185, v156, vcc
	v_pk_mul_f32 v[156:157], v[106:107], s[14:15] op_sel_hi:[1,0]
	v_cmp_le_u32_e32 vcc, v162, v195
	v_max3_f32 v160, v160, v158, v159
	s_nop 0
	v_cndmask_b32_e32 v157, v185, v157, vcc
	v_cmp_le_u32_e32 vcc, v161, v195
	s_nop 1
	v_cndmask_b32_e32 v156, v185, v156, vcc
	v_max3_f32 v162, v160, v156, v157
	v_pk_mul_f32 v[160:161], v[108:109], s[14:15] op_sel_hi:[1,0]
	v_cmp_le_u32_e32 vcc, v164, v195
	s_nop 1
	v_cndmask_b32_e32 v161, v185, v161, vcc
	v_cmp_le_u32_e32 vcc, v163, v195
	s_nop 1
	v_cndmask_b32_e32 v160, v185, v160, vcc
	v_max3_f32 v164, v162, v160, v161
	v_pk_mul_f32 v[162:163], v[110:111], s[14:15] op_sel_hi:[1,0]
	v_cmp_le_u32_e32 vcc, v197, v195
	s_nop 1
	v_cndmask_b32_e32 v163, v185, v163, vcc
	v_cmp_le_u32_e32 vcc, v165, v195
	s_nop 1
	v_cndmask_b32_e32 v162, v185, v162, vcc
	v_max3_f32 v197, v164, v162, v163
	v_pk_mul_f32 v[164:165], v[112:113], s[14:15] op_sel_hi:[1,0]
	v_cmp_le_u32_e32 vcc, v196, v195
	s_nop 1
	v_cndmask_b32_e32 v165, v185, v165, vcc
	v_cmp_le_u32_e32 vcc, v198, v195
	s_nop 1
	v_cndmask_b32_e32 v164, v185, v164, vcc
	v_max3_f32 v195, v197, v164, v165
	s_cbranch_execnz .LBB0_2562
